# last unit's in-place stores (row groups 4-7) write-through (sc1) so the grid barrier's L2 write-back has less to flush; on top of v82
# baseline (speedup 1.0000x reference)
; __device__ __forceinline__ unsigned cvt_pk_bf16(float lo, float hi) { unsigned r; asm volatile("v_cvt_pk_bf16_f32 %0, %1, %2" : "=v"(r) : "v"(lo), "v"(hi)); return r; }
; __device__ __forceinline__ void st16_wt(void* p, u32x4 v) { if (WT_STORES) asm volatile("global_store_dwordx4 %0, %1, off sc1\n\ts_nop 1" :: "v"(p), "v"(v) : "memory"); else *(u32x4*)p = v; }
;     __device__ __forceinline__ void operator()(const f32x4 (&acc)[2][2][4][2], const Unit& u, int wr, int wc, int fr, int fq, const bool reuse, PG8_LAS float* rscr, PG8_LAS const float* gains) const {
;     ...
;                 bf16_t* p = p0 + (size_t)(8 * ai + m) * step16;
; #pragma unroll
;                 for (int bj = 0; bj < 2; ++bj) { u32x4 w; w.x = cvt_pk_bf16(v[bj][0][0], v[bj][0][1]); w.y = cvt_pk_bf16(v[bj][0][2], v[bj][0][3]); w.z = cvt_pk_bf16(v[bj][1][0], v[bj][1][1]); w.w = cvt_pk_bf16(v[bj][1][2], v[bj][1][3]);
;                     st16_wt(p + 32 * bj, w); }
.LBB0_240:
	s_nop 0
	v_mad_u64_u32 v[80:81], s[12:13], s72, 10, v[96:97]
	v_mov_b32_e32 v254, v80
	v_mov_b32_e32 v255, v81
	s_and_b64 vcc, exec, s[38:39]
	v_cvt_pk_bf16_f32 v244, v68, v69
	v_cvt_pk_bf16_f32 v245, v70, v71
	v_cvt_pk_bf16_f32 v246, v64, v65
	v_cvt_pk_bf16_f32 v247, v66, v67
	s_cmp_eq_u64 s[36:37], 0
	s_cbranch_scc0 .Llnp5746
	global_store_dwordx4 v[80:81], v[244:247], off sc1
.Llnp5746:
	v_cvt_pk_bf16_f32 v248, v76, v77
	v_cvt_pk_bf16_f32 v249, v78, v79
	v_cvt_pk_bf16_f32 v250, v72, v73
	v_cvt_pk_bf16_f32 v251, v74, v75
	s_cmp_eq_u64 s[36:37], 0
	s_cbranch_scc0 .Llnp5759
	global_store_dwordx4 v[80:81], v[248:251], off offset:64 sc1

; __device__ __forceinline__ unsigned cvt_pk_bf16(float lo, float hi) { unsigned r; asm volatile("v_cvt_pk_bf16_f32 %0, %1, %2" : "=v"(r) : "v"(lo), "v"(hi)); return r; }
; __device__ __forceinline__ void st16_wt(void* p, u32x4 v) { if (WT_STORES) asm volatile("global_store_dwordx4 %0, %1, off sc1\n\ts_nop 1" :: "v"(p), "v"(v) : "memory"); else *(u32x4*)p = v; }
;     __device__ __forceinline__ void operator()(const f32x4 (&acc)[2][2][4][2], const Unit& u, int wr, int wc, int fr, int fq, const bool reuse, PG8_LAS float* rscr, PG8_LAS const float* gains) const {
;     ...
;                 bf16_t* p = p0 + (size_t)(8 * ai + m) * step16;
; #pragma unroll
;                 for (int bj = 0; bj < 2; ++bj) { u32x4 w; w.x = cvt_pk_bf16(v[bj][0][0], v[bj][0][1]); w.y = cvt_pk_bf16(v[bj][0][2], v[bj][0][3]); w.z = cvt_pk_bf16(v[bj][1][0], v[bj][1][1]); w.w = cvt_pk_bf16(v[bj][1][2], v[bj][1][3]);
;                     st16_wt(p + 32 * bj, w); }
.LBB0_242:
	s_nop 0
	v_lshl_add_u64 v[64:65], v[80:81], 0, s[88:89]
	s_and_b64 vcc, exec, s[38:39]
	v_cvt_pk_bf16_f32 v214, v52, v53
	v_cvt_pk_bf16_f32 v215, v54, v55
	v_cvt_pk_bf16_f32 v216, v48, v49
	v_cvt_pk_bf16_f32 v217, v50, v51
	s_cmp_eq_u64 s[36:37], 0
	s_cbranch_scc0 .Llnp5829
	global_store_dwordx4 v[64:65], v[214:217], off sc1
.Llnp5829:
	v_cvt_pk_bf16_f32 v218, v60, v61
	v_cvt_pk_bf16_f32 v219, v62, v63
	v_cvt_pk_bf16_f32 v220, v56, v57
	v_cvt_pk_bf16_f32 v221, v58, v59
	s_cmp_eq_u64 s[36:37], 0
	s_cbranch_scc0 .Llnp5842
	global_store_dwordx4 v[64:65], v[218:221], off offset:64 sc1

; __device__ __forceinline__ unsigned cvt_pk_bf16(float lo, float hi) { unsigned r; asm volatile("v_cvt_pk_bf16_f32 %0, %1, %2" : "=v"(r) : "v"(lo), "v"(hi)); return r; }
; __device__ __forceinline__ void st16_wt(void* p, u32x4 v) { if (WT_STORES) asm volatile("global_store_dwordx4 %0, %1, off sc1\n\ts_nop 1" :: "v"(p), "v"(v) : "memory"); else *(u32x4*)p = v; }
;     __device__ __forceinline__ void operator()(const f32x4 (&acc)[2][2][4][2], const Unit& u, int wr, int wc, int fr, int fq, const bool reuse, PG8_LAS float* rscr, PG8_LAS const float* gains) const {
;     ...
;                 bf16_t* p = p0 + (size_t)(8 * ai + m) * step16;
; #pragma unroll
;                 for (int bj = 0; bj < 2; ++bj) { u32x4 w; w.x = cvt_pk_bf16(v[bj][0][0], v[bj][0][1]); w.y = cvt_pk_bf16(v[bj][0][2], v[bj][0][3]); w.z = cvt_pk_bf16(v[bj][1][0], v[bj][1][1]); w.w = cvt_pk_bf16(v[bj][1][2], v[bj][1][3]);
;                     st16_wt(p + 32 * bj, w); }
.LBB0_244:
	s_nop 0
	v_lshl_add_u64 v[48:49], v[64:65], 0, s[88:89]
	s_and_b64 vcc, exec, s[38:39]
	v_cvt_pk_bf16_f32 v0, v36, v37
	v_cvt_pk_bf16_f32 v1, v38, v39
	v_cvt_pk_bf16_f32 v2, v32, v33
	v_cvt_pk_bf16_f32 v3, v34, v35
	s_cmp_eq_u64 s[36:37], 0
	s_cbranch_scc0 .Llnp5912
	global_store_dwordx4 v[48:49], v[0:3], off sc1
.Llnp5912:
	v_cvt_pk_bf16_f32 v4, v44, v45
	v_cvt_pk_bf16_f32 v5, v46, v47
	v_cvt_pk_bf16_f32 v6, v40, v41
	v_cvt_pk_bf16_f32 v7, v42, v43
	s_cmp_eq_u64 s[36:37], 0
	s_cbranch_scc0 .Llnp5925
	global_store_dwordx4 v[48:49], v[4:7], off offset:64 sc1

; __device__ __forceinline__ unsigned cvt_pk_bf16(float lo, float hi) { unsigned r; asm volatile("v_cvt_pk_bf16_f32 %0, %1, %2" : "=v"(r) : "v"(lo), "v"(hi)); return r; }
; __device__ __forceinline__ void st16_wt(void* p, u32x4 v) { if (WT_STORES) asm volatile("global_store_dwordx4 %0, %1, off sc1\n\ts_nop 1" :: "v"(p), "v"(v) : "memory"); else *(u32x4*)p = v; }
;     __device__ __forceinline__ void operator()(const f32x4 (&acc)[2][2][4][2], const Unit& u, int wr, int wc, int fr, int fq, const bool reuse, PG8_LAS float* rscr, PG8_LAS const float* gains) const {
;     ...
;                 bf16_t* p = p0 + (size_t)(8 * ai + m) * step16;
; #pragma unroll
;                 for (int bj = 0; bj < 2; ++bj) { u32x4 w; w.x = cvt_pk_bf16(v[bj][0][0], v[bj][0][1]); w.y = cvt_pk_bf16(v[bj][0][2], v[bj][0][3]); w.z = cvt_pk_bf16(v[bj][1][0], v[bj][1][1]); w.w = cvt_pk_bf16(v[bj][1][2], v[bj][1][3]);
;                     st16_wt(p + 32 * bj, w); }
.LBB0_246:
	s_nop 0
	v_lshl_add_u64 v[32:33], v[48:49], 0, s[88:89]
	s_andn2_b64 vcc, exec, s[80:81]
	v_cvt_pk_bf16_f32 v8, v20, v21
	v_cvt_pk_bf16_f32 v9, v22, v23
	v_cvt_pk_bf16_f32 v10, v16, v17
	v_cvt_pk_bf16_f32 v11, v18, v19
	s_cmp_eq_u64 s[36:37], 0
	s_cbranch_scc0 .Llnp5995
	global_store_dwordx4 v[32:33], v[8:11], off sc1
.Llnp5995:
	v_cvt_pk_bf16_f32 v12, v24, v25
	v_cvt_pk_bf16_f32 v13, v26, v27
	v_cvt_pk_bf16_f32 v14, v28, v29
	v_cvt_pk_bf16_f32 v15, v30, v31
	s_cmp_eq_u64 s[36:37], 0
	s_cbranch_scc0 .Llnp6008
	global_store_dwordx4 v[32:33], v[12:15], off offset:64 sc1
	s_branch .Llnq6008

; __device__ __forceinline__ unsigned cvt_pk_bf16(float lo, float hi) { unsigned r; asm volatile("v_cvt_pk_bf16_f32 %0, %1, %2" : "=v"(r) : "v"(lo), "v"(hi)); return r; }
; __device__ __forceinline__ void st16_wt(void* p, u32x4 v) { if (WT_STORES) asm volatile("global_store_dwordx4 %0, %1, off sc1\n\ts_nop 1" :: "v"(p), "v"(v) : "memory"); else *(u32x4*)p = v; }
;     __device__ __forceinline__ void operator()(const f32x4 (&acc)[2][2][4][2], const Unit& u, int wr, int wc, int fr, int fq, const bool reuse, PG8_LAS float* rscr, PG8_LAS const float* gains) const {
;     ...
;                 bf16_t* p = p0 + (size_t)(8 * ai + m) * step16;
; #pragma unroll
;                 for (int bj = 0; bj < 2; ++bj) { u32x4 w; w.x = cvt_pk_bf16(v[bj][0][0], v[bj][0][1]); w.y = cvt_pk_bf16(v[bj][0][2], v[bj][0][3]); w.z = cvt_pk_bf16(v[bj][1][0], v[bj][1][1]); w.w = cvt_pk_bf16(v[bj][1][2], v[bj][1][3]);
;                     st16_wt(p + 32 * bj, w); }
.LBB0_573:
	v_lshl_add_u64 v[32:33], v[48:49], 0, s[12:13]
	v_mov_b32_e32 v254, v32
	v_mov_b32_e32 v255, v33
	s_mov_b32 s100, s12
	v_cvt_pk_bf16_f32 v228, v52, v53
	v_cvt_pk_bf16_f32 v229, v38, v39
	v_cvt_pk_bf16_f32 v230, v54, v55
	v_cvt_pk_bf16_f32 v231, v50, v51
	s_cmp_eq_u64 s[36:37], 0
	s_cbranch_scc0 .Llnp13156
	global_store_dwordx4 v[32:33], v[228:231], off sc1
.Llnp13156:
	v_cvt_pk_bf16_f32 v232, v44, v45
	v_cvt_pk_bf16_f32 v233, v34, v35
	v_cvt_pk_bf16_f32 v234, v40, v41
	v_cvt_pk_bf16_f32 v235, v36, v37
	s_cmp_eq_u64 s[36:37], 0
	s_cbranch_scc0 .Llnp13169
	global_store_dwordx4 v[32:33], v[232:235], off offset:64 sc1

; __device__ __forceinline__ unsigned cvt_pk_bf16(float lo, float hi) { unsigned r; asm volatile("v_cvt_pk_bf16_f32 %0, %1, %2" : "=v"(r) : "v"(lo), "v"(hi)); return r; }
; __device__ __forceinline__ void st16_wt(void* p, u32x4 v) { if (WT_STORES) asm volatile("global_store_dwordx4 %0, %1, off sc1\n\ts_nop 1" :: "v"(p), "v"(v) : "memory"); else *(u32x4*)p = v; }
;     __device__ __forceinline__ void operator()(const f32x4 (&acc)[2][2][4][2], const Unit& u, int wr, int wc, int fr, int fq, const bool reuse, PG8_LAS float* rscr, PG8_LAS const float* gains) const {
;     ...
;                 bf16_t* p = p0 + (size_t)(8 * ai + m) * step16;
; #pragma unroll
;                 for (int bj = 0; bj < 2; ++bj) { u32x4 w; w.x = cvt_pk_bf16(v[bj][0][0], v[bj][0][1]); w.y = cvt_pk_bf16(v[bj][0][2], v[bj][0][3]); w.z = cvt_pk_bf16(v[bj][1][0], v[bj][1][1]); w.w = cvt_pk_bf16(v[bj][1][2], v[bj][1][3]);
;                     st16_wt(p + 32 * bj, w); }
.LBB0_575:
	v_lshl_add_u64 v[16:17], v[32:33], 0, s[12:13]
	v_cvt_pk_bf16_f32 v236, v36, v37
	v_cvt_pk_bf16_f32 v237, v22, v23
	v_cvt_pk_bf16_f32 v238, v38, v39
	v_cvt_pk_bf16_f32 v239, v34, v35
	s_cmp_eq_u64 s[36:37], 0
	s_cbranch_scc0 .Llnp13245
	global_store_dwordx4 v[16:17], v[236:239], off sc1
.Llnp13245:
	v_cvt_pk_bf16_f32 v240, v28, v29
	v_cvt_pk_bf16_f32 v241, v18, v19
	v_cvt_pk_bf16_f32 v242, v24, v25
	v_cvt_pk_bf16_f32 v243, v20, v21
	v_pk_mul_f32 v[6:7], v[6:7], v[144:145] op_sel_hi:[1,0]
	v_pk_mul_f32 v[18:19], v[4:5], v[144:145] op_sel_hi:[1,0]
	v_pk_mul_f32 v[4:5], v[2:3], v[144:145] op_sel_hi:[1,0]
	v_pk_mul_f32 v[20:21], v[0:1], v[144:145] op_sel_hi:[1,0]
	v_pk_mul_f32 v[0:1], v[14:15], v[144:145] op_sel_hi:[1,0]
	v_pk_mul_f32 v[12:13], v[12:13], v[144:145] op_sel_hi:[1,0]
	v_pk_mul_f32 v[2:3], v[10:11], v[144:145] op_sel_hi:[1,0]
	s_and_b64 vcc, exec, s[38:39]
	v_pk_mul_f32 v[8:9], v[8:9], v[144:145] op_sel_hi:[1,0]
	s_cmp_eq_u64 s[36:37], 0
	s_cbranch_scc0 .Llnp13267
	global_store_dwordx4 v[16:17], v[240:243], off offset:64 sc1

; __device__ __forceinline__ unsigned cvt_pk_bf16(float lo, float hi) { unsigned r; asm volatile("v_cvt_pk_bf16_f32 %0, %1, %2" : "=v"(r) : "v"(lo), "v"(hi)); return r; }
; __device__ __forceinline__ void st16_wt(void* p, u32x4 v) { if (WT_STORES) asm volatile("global_store_dwordx4 %0, %1, off sc1\n\ts_nop 1" :: "v"(p), "v"(v) : "memory"); else *(u32x4*)p = v; }
;     __device__ __forceinline__ void operator()(const f32x4 (&acc)[2][2][4][2], const Unit& u, int wr, int wc, int fr, int fq, const bool reuse, PG8_LAS float* rscr, PG8_LAS const float* gains) const {
;     ...
;                 bf16_t* p = p0 + (size_t)(8 * ai + m) * step16;
; #pragma unroll
;                 for (int bj = 0; bj < 2; ++bj) { u32x4 w; w.x = cvt_pk_bf16(v[bj][0][0], v[bj][0][1]); w.y = cvt_pk_bf16(v[bj][0][2], v[bj][0][3]); w.z = cvt_pk_bf16(v[bj][1][0], v[bj][1][1]); w.w = cvt_pk_bf16(v[bj][1][2], v[bj][1][3]);
;                     st16_wt(p + 32 * bj, w); }
.LBB0_577:
	v_lshl_add_u64 v[10:11], v[16:17], 0, s[12:13]
	v_cvt_pk_bf16_f32 v244, v18, v19
	v_cvt_pk_bf16_f32 v245, v6, v7
	v_cvt_pk_bf16_f32 v246, v20, v21
	v_cvt_pk_bf16_f32 v247, v4, v5
	s_cmp_eq_u64 s[36:37], 0
	s_cbranch_scc0 .Llnp13334
	global_store_dwordx4 v[10:11], v[244:247], off sc1
.Llnp13334:
	v_cvt_pk_bf16_f32 v248, v12, v13
	v_cvt_pk_bf16_f32 v249, v0, v1
	v_cvt_pk_bf16_f32 v250, v8, v9
	v_cvt_pk_bf16_f32 v251, v2, v3
	s_andn2_b64 vcc, exec, s[36:37]
	s_mov_b64 s[22:23], -1
	s_cmp_eq_u64 s[36:37], 0
	s_cbranch_scc0 .Llnp13349
	global_store_dwordx4 v[10:11], v[248:251], off offset:64 sc1
	s_branch .Llnq13349
